# combo9_ntst
# speedup vs baseline: 1.0144x; 1.0063x over previous
.LBB0_281:
	s_andn2_b64 vcc, exec, s[30:31]
	s_cbranch_vccnz .LBB0_283
	v_readlane_b32 s4, v254, 24
	s_add_u32 s4, s4, s42
	v_readlane_b32 s5, v254, 25
	s_addc_u32 s5, s5, s43
	v_lshlrev_b32_e32 v0, 2, v137
	v_lshl_add_u64 v[140:141], s[4:5], 0, v[0:1]
	v_ashrrev_i32_e32 v133, 31, v132
	v_lshl_add_u64 v[140:141], v[132:133], 2, v[140:141]
	global_store_dwordx4 v[140:141], v[126:129], off nt

.LBB0_288:
	s_andn2_b64 vcc, exec, s[4:5]
	s_cbranch_vccnz .LBB0_292
	v_cmp_gt_i32_e32 vcc, 32, v132
	s_and_saveexec_b64 s[4:5], vcc
	s_cbranch_execz .LBB0_291
	v_ashrrev_i32_e32 v133, 31, v132
	v_lshl_add_u64 v[140:141], v[132:133], 2, v[138:139]
	global_store_dwordx4 v[140:141], v[126:129], off nt

.LBB0_308:
	s_andn2_b64 vcc, exec, s[8:9]
	s_cbranch_vccnz .LBB0_312
	s_andn2_b64 vcc, exec, s[30:31]
	s_cbranch_vccnz .LBB0_311
	v_readlane_b32 s8, v254, 24
	s_add_u32 s8, s8, s42
	v_readlane_b32 s9, v254, 25
	s_addc_u32 s9, s9, s43
	v_lshlrev_b32_e32 v0, 2, v137
	s_ashr_i32 s39, s38, 31
	v_ashrrev_i32_e32 v131, 31, v130
	v_lshl_add_u64 v[126:127], s[8:9], 0, v[0:1]
	v_lshl_add_u64 v[128:129], v[130:131], 0, s[38:39]
	v_lshl_add_u64 v[126:127], v[128:129], 2, v[126:127]
	global_store_dwordx4 v[126:127], v[122:125], off offset:64 nt

.LBB0_316:
	s_andn2_b64 vcc, exec, s[8:9]
	s_cbranch_vccnz .LBB0_320
	v_cmp_gt_i32_e32 vcc, 32, v144
	s_and_saveexec_b64 s[8:9], vcc
	s_cbranch_execz .LBB0_319
	s_ashr_i32 s39, s38, 31
	v_ashrrev_i32_e32 v131, 31, v130
	v_lshl_add_u64 v[126:127], v[130:131], 0, s[38:39]
	v_lshl_add_u64 v[126:127], v[126:127], 2, v[138:139]
	global_store_dwordx4 v[126:127], v[122:125], off offset:64 nt

.LBB0_334:
	s_andn2_b64 vcc, exec, s[8:9]
	s_cbranch_vccnz .LBB0_338
	s_andn2_b64 vcc, exec, s[30:31]
	s_cbranch_vccnz .LBB0_337
	v_readlane_b32 s8, v254, 24
	s_add_u32 s8, s8, s42
	v_readlane_b32 s9, v254, 25
	s_addc_u32 s9, s9, s43
	v_lshlrev_b32_e32 v0, 2, v137
	s_ashr_i32 s39, s38, 31
	v_ashrrev_i32_e32 v131, 31, v130
	v_lshl_add_u64 v[122:123], s[8:9], 0, v[0:1]
	v_lshl_add_u64 v[124:125], v[130:131], 0, s[38:39]
	v_lshl_add_u64 v[122:123], v[124:125], 2, v[122:123]
	global_store_dwordx4 v[122:123], v[118:121], off offset:128 nt

.LBB0_342:
	s_andn2_b64 vcc, exec, s[8:9]
	s_cbranch_vccnz .LBB0_346
	v_cmp_gt_i32_e32 vcc, 32, v140
	s_and_saveexec_b64 s[8:9], vcc
	s_cbranch_execz .LBB0_345
	s_ashr_i32 s39, s38, 31
	v_ashrrev_i32_e32 v131, 31, v130
	v_lshl_add_u64 v[122:123], v[130:131], 0, s[38:39]
	v_lshl_add_u64 v[122:123], v[122:123], 2, v[138:139]
	global_store_dwordx4 v[122:123], v[118:121], off offset:128 nt

.LBB0_360:
	s_andn2_b64 vcc, exec, s[8:9]
	s_cbranch_vccnz .LBB0_364
	s_andn2_b64 vcc, exec, s[30:31]
	s_cbranch_vccnz .LBB0_363
	v_readlane_b32 s8, v254, 24
	s_add_u32 s8, s8, s42
	v_readlane_b32 s9, v254, 25
	s_addc_u32 s9, s9, s43
	v_lshlrev_b32_e32 v0, 2, v137
	s_ashr_i32 s39, s38, 31
	v_ashrrev_i32_e32 v131, 31, v130
	v_lshl_add_u64 v[118:119], s[8:9], 0, v[0:1]
	v_lshl_add_u64 v[120:121], v[130:131], 0, s[38:39]
	v_lshl_add_u64 v[118:119], v[120:121], 2, v[118:119]
	global_store_dwordx4 v[118:119], v[114:117], off offset:192 nt

.LBB0_368:
	s_andn2_b64 vcc, exec, s[8:9]
	s_cbranch_vccnz .LBB0_372
	v_cmp_gt_i32_e32 vcc, 32, v126
	s_and_saveexec_b64 s[8:9], vcc
	s_cbranch_execz .LBB0_371
	s_ashr_i32 s39, s38, 31
	v_ashrrev_i32_e32 v131, 31, v130
	v_lshl_add_u64 v[118:119], v[130:131], 0, s[38:39]
	v_lshl_add_u64 v[118:119], v[118:119], 2, v[138:139]
	global_store_dwordx4 v[118:119], v[114:117], off offset:192 nt

.LBB0_390:
	s_andn2_b64 vcc, exec, s[30:31]
	s_cbranch_vccnz .LBB0_392
	v_readlane_b32 s29, v254, 24
	s_add_u32 s68, s29, s42
	v_readlane_b32 s29, v254, 25
	s_addc_u32 s69, s29, s43
	v_lshlrev_b32_e32 v0, 2, v128
	v_lshl_add_u64 v[120:121], s[68:69], 0, v[0:1]
	v_ashrrev_i32_e32 v133, 31, v132
	v_lshl_add_u64 v[120:121], v[132:133], 2, v[120:121]
	global_store_dwordx4 v[120:121], v[110:113], off nt

.LBB0_397:
	s_andn2_b64 vcc, exec, s[68:69]
	s_cbranch_vccnz .LBB0_401
	v_cmp_gt_i32_e32 vcc, 32, v132
	s_and_saveexec_b64 s[68:69], vcc
	s_cbranch_execz .LBB0_400
	v_ashrrev_i32_e32 v133, 31, v132
	v_lshl_add_u64 v[120:121], v[132:133], 2, v[118:119]
	global_store_dwordx4 v[120:121], v[110:113], off nt

.LBB0_415:
	s_andn2_b64 vcc, exec, s[68:69]
	s_cbranch_vccnz .LBB0_419
	s_andn2_b64 vcc, exec, s[30:31]
	s_cbranch_vccnz .LBB0_418
	v_readlane_b32 s29, v254, 24
	s_add_u32 s68, s29, s42
	v_readlane_b32 s29, v254, 25
	s_addc_u32 s69, s29, s43
	v_lshlrev_b32_e32 v0, 2, v128
	s_ashr_i32 s39, s38, 31
	v_ashrrev_i32_e32 v131, 31, v130
	v_lshl_add_u64 v[110:111], s[68:69], 0, v[0:1]
	v_lshl_add_u64 v[112:113], v[130:131], 0, s[38:39]
	v_lshl_add_u64 v[110:111], v[112:113], 2, v[110:111]
	global_store_dwordx4 v[110:111], v[106:109], off offset:64 nt

.LBB0_423:
	s_andn2_b64 vcc, exec, s[68:69]
	s_cbranch_vccnz .LBB0_427
	v_cmp_gt_i32_e32 vcc, 32, v144
	s_and_saveexec_b64 s[68:69], vcc
	s_cbranch_execz .LBB0_426
	s_ashr_i32 s39, s38, 31
	v_ashrrev_i32_e32 v131, 31, v130
	v_lshl_add_u64 v[110:111], v[130:131], 0, s[38:39]
	v_lshl_add_u64 v[110:111], v[110:111], 2, v[118:119]
	global_store_dwordx4 v[110:111], v[106:109], off offset:64 nt

.LBB0_441:
	s_andn2_b64 vcc, exec, s[68:69]
	s_cbranch_vccnz .LBB0_445
	s_andn2_b64 vcc, exec, s[30:31]
	s_cbranch_vccnz .LBB0_444
	v_readlane_b32 s29, v254, 24
	s_add_u32 s68, s29, s42
	v_readlane_b32 s29, v254, 25
	s_addc_u32 s69, s29, s43
	v_lshlrev_b32_e32 v0, 2, v128
	s_ashr_i32 s39, s38, 31
	v_ashrrev_i32_e32 v131, 31, v130
	v_lshl_add_u64 v[106:107], s[68:69], 0, v[0:1]
	v_lshl_add_u64 v[108:109], v[130:131], 0, s[38:39]
	v_lshl_add_u64 v[106:107], v[108:109], 2, v[106:107]
	global_store_dwordx4 v[106:107], v[102:105], off offset:128 nt

.LBB0_449:
	s_andn2_b64 vcc, exec, s[68:69]
	s_cbranch_vccnz .LBB0_453
	v_cmp_gt_i32_e32 vcc, 32, v140
	s_and_saveexec_b64 s[68:69], vcc
	s_cbranch_execz .LBB0_452
	s_ashr_i32 s39, s38, 31
	v_ashrrev_i32_e32 v131, 31, v130
	v_lshl_add_u64 v[106:107], v[130:131], 0, s[38:39]
	v_lshl_add_u64 v[106:107], v[106:107], 2, v[118:119]
	global_store_dwordx4 v[106:107], v[102:105], off offset:128 nt

.LBB0_467:
	s_andn2_b64 vcc, exec, s[68:69]
	s_cbranch_vccnz .LBB0_471
	s_andn2_b64 vcc, exec, s[30:31]
	s_cbranch_vccnz .LBB0_470
	v_readlane_b32 s29, v254, 24
	s_add_u32 s68, s29, s42
	v_readlane_b32 s29, v254, 25
	s_addc_u32 s69, s29, s43
	v_lshlrev_b32_e32 v0, 2, v128
	s_ashr_i32 s39, s38, 31
	v_ashrrev_i32_e32 v131, 31, v130
	v_lshl_add_u64 v[102:103], s[68:69], 0, v[0:1]
	v_lshl_add_u64 v[104:105], v[130:131], 0, s[38:39]
	v_lshl_add_u64 v[102:103], v[104:105], 2, v[102:103]
	global_store_dwordx4 v[102:103], v[98:101], off offset:192 nt

.LBB0_475:
	s_andn2_b64 vcc, exec, s[68:69]
	s_cbranch_vccnz .LBB0_479
	v_cmp_gt_i32_e32 vcc, 32, v126
	s_and_saveexec_b64 s[68:69], vcc
	s_cbranch_execz .LBB0_478
	s_ashr_i32 s39, s38, 31
	v_ashrrev_i32_e32 v131, 31, v130
	v_lshl_add_u64 v[102:103], v[130:131], 0, s[38:39]
	v_lshl_add_u64 v[102:103], v[102:103], 2, v[118:119]
	global_store_dwordx4 v[102:103], v[98:101], off offset:192 nt

.LBB0_511:
	s_andn2_b64 vcc, exec, s[30:31]
	s_cbranch_vccnz .LBB0_513
	v_readlane_b32 s29, v254, 24
	s_add_u32 s68, s29, s42
	v_readlane_b32 s29, v254, 25
	s_addc_u32 s69, s29, s43
	v_lshlrev_b32_e32 v0, 2, v109
	v_lshl_add_u64 v[102:103], s[68:69], 0, v[0:1]
	v_ashrrev_i32_e32 v133, 31, v132
	v_lshl_add_u64 v[102:103], v[132:133], 2, v[102:103]
	global_store_dwordx4 v[102:103], v[94:97], off nt

.LBB0_518:
	s_andn2_b64 vcc, exec, s[68:69]
	s_cbranch_vccnz .LBB0_522
	v_cmp_gt_i32_e32 vcc, 32, v132
	s_and_saveexec_b64 s[68:69], vcc
	s_cbranch_execz .LBB0_521
	v_ashrrev_i32_e32 v133, 31, v132
	v_lshl_add_u64 v[102:103], v[132:133], 2, v[100:101]
	global_store_dwordx4 v[102:103], v[94:97], off nt

.LBB0_536:
	s_andn2_b64 vcc, exec, s[68:69]
	s_cbranch_vccnz .LBB0_540
	s_andn2_b64 vcc, exec, s[30:31]
	s_cbranch_vccnz .LBB0_539
	v_readlane_b32 s29, v254, 24
	s_add_u32 s68, s29, s42
	v_readlane_b32 s29, v254, 25
	s_addc_u32 s69, s29, s43
	v_lshlrev_b32_e32 v0, 2, v109
	s_ashr_i32 s39, s38, 31
	v_ashrrev_i32_e32 v131, 31, v130
	v_lshl_add_u64 v[94:95], s[68:69], 0, v[0:1]
	v_lshl_add_u64 v[96:97], v[130:131], 0, s[38:39]
	v_lshl_add_u64 v[94:95], v[96:97], 2, v[94:95]
	global_store_dwordx4 v[94:95], v[90:93], off offset:64 nt

.LBB0_544:
	s_andn2_b64 vcc, exec, s[68:69]
	s_cbranch_vccnz .LBB0_548
	v_cmp_gt_i32_e32 vcc, 32, v144
	s_and_saveexec_b64 s[68:69], vcc
	s_cbranch_execz .LBB0_547
	s_ashr_i32 s39, s38, 31
	v_ashrrev_i32_e32 v131, 31, v130
	v_lshl_add_u64 v[94:95], v[130:131], 0, s[38:39]
	v_lshl_add_u64 v[94:95], v[94:95], 2, v[100:101]
	global_store_dwordx4 v[94:95], v[90:93], off offset:64 nt

.LBB0_562:
	s_andn2_b64 vcc, exec, s[68:69]
	s_cbranch_vccnz .LBB0_566
	s_andn2_b64 vcc, exec, s[30:31]
	s_cbranch_vccnz .LBB0_565
	v_readlane_b32 s29, v254, 24
	s_add_u32 s68, s29, s42
	v_readlane_b32 s29, v254, 25
	s_addc_u32 s69, s29, s43
	v_lshlrev_b32_e32 v0, 2, v109
	s_ashr_i32 s39, s38, 31
	v_ashrrev_i32_e32 v131, 31, v130
	v_lshl_add_u64 v[90:91], s[68:69], 0, v[0:1]
	v_lshl_add_u64 v[92:93], v[130:131], 0, s[38:39]
	v_lshl_add_u64 v[90:91], v[92:93], 2, v[90:91]
	global_store_dwordx4 v[90:91], v[86:89], off offset:128 nt

.LBB0_570:
	s_andn2_b64 vcc, exec, s[68:69]
	s_cbranch_vccnz .LBB0_574
	v_cmp_gt_i32_e32 vcc, 32, v140
	s_and_saveexec_b64 s[68:69], vcc
	s_cbranch_execz .LBB0_573
	s_ashr_i32 s39, s38, 31
	v_ashrrev_i32_e32 v131, 31, v130
	v_lshl_add_u64 v[90:91], v[130:131], 0, s[38:39]
	v_lshl_add_u64 v[90:91], v[90:91], 2, v[100:101]
	global_store_dwordx4 v[90:91], v[86:89], off offset:128 nt

.LBB0_588:
	s_andn2_b64 vcc, exec, s[68:69]
	s_cbranch_vccnz .LBB0_592
	s_andn2_b64 vcc, exec, s[30:31]
	s_cbranch_vccnz .LBB0_591
	v_readlane_b32 s29, v254, 24
	s_add_u32 s68, s29, s42
	v_readlane_b32 s29, v254, 25
	s_addc_u32 s69, s29, s43
	v_lshlrev_b32_e32 v0, 2, v109
	s_ashr_i32 s39, s38, 31
	v_ashrrev_i32_e32 v131, 31, v130
	v_lshl_add_u64 v[86:87], s[68:69], 0, v[0:1]
	v_lshl_add_u64 v[88:89], v[130:131], 0, s[38:39]
	v_lshl_add_u64 v[86:87], v[88:89], 2, v[86:87]
	global_store_dwordx4 v[86:87], v[82:85], off offset:192 nt

.LBB0_596:
	s_andn2_b64 vcc, exec, s[68:69]
	s_cbranch_vccnz .LBB0_600
	v_cmp_gt_i32_e32 vcc, 32, v126
	s_and_saveexec_b64 s[68:69], vcc
	s_cbranch_execz .LBB0_599
	s_ashr_i32 s39, s38, 31
	v_ashrrev_i32_e32 v131, 31, v130
	v_lshl_add_u64 v[86:87], v[130:131], 0, s[38:39]
	v_lshl_add_u64 v[86:87], v[86:87], 2, v[100:101]
	global_store_dwordx4 v[86:87], v[82:85], off offset:192 nt

.LBB0_626:
	s_andn2_b64 vcc, exec, s[30:31]
	s_cbranch_vccnz .LBB0_628
	v_readlane_b32 s29, v254, 24
	s_add_u32 s68, s29, s42
	v_readlane_b32 s29, v254, 25
	s_addc_u32 s69, s29, s43
	v_lshlrev_b32_e32 v0, 2, v92
	v_lshl_add_u64 v[86:87], s[68:69], 0, v[0:1]
	v_ashrrev_i32_e32 v133, 31, v132
	v_lshl_add_u64 v[86:87], v[132:133], 2, v[86:87]
	global_store_dwordx4 v[86:87], v[78:81], off nt

.LBB0_633:
	s_andn2_b64 vcc, exec, s[68:69]
	s_cbranch_vccnz .LBB0_637
	v_cmp_gt_i32_e32 vcc, 32, v132
	s_and_saveexec_b64 s[68:69], vcc
	s_cbranch_execz .LBB0_636
	v_ashrrev_i32_e32 v133, 31, v132
	v_lshl_add_u64 v[86:87], v[132:133], 2, v[84:85]
	global_store_dwordx4 v[86:87], v[78:81], off nt

.LBB0_651:
	s_andn2_b64 vcc, exec, s[68:69]
	s_cbranch_vccnz .LBB0_655
	s_andn2_b64 vcc, exec, s[30:31]
	s_cbranch_vccnz .LBB0_654
	v_readlane_b32 s29, v254, 24
	s_add_u32 s68, s29, s42
	v_readlane_b32 s29, v254, 25
	s_addc_u32 s69, s29, s43
	v_lshlrev_b32_e32 v0, 2, v92
	s_ashr_i32 s39, s38, 31
	v_ashrrev_i32_e32 v131, 31, v130
	v_lshl_add_u64 v[78:79], s[68:69], 0, v[0:1]
	v_lshl_add_u64 v[80:81], v[130:131], 0, s[38:39]
	v_lshl_add_u64 v[78:79], v[80:81], 2, v[78:79]
	global_store_dwordx4 v[78:79], v[74:77], off offset:64 nt

.LBB0_659:
	s_andn2_b64 vcc, exec, s[68:69]
	s_cbranch_vccnz .LBB0_663
	v_cmp_gt_i32_e32 vcc, 32, v144
	s_and_saveexec_b64 s[68:69], vcc
	s_cbranch_execz .LBB0_662
	s_ashr_i32 s39, s38, 31
	v_ashrrev_i32_e32 v131, 31, v130
	v_lshl_add_u64 v[78:79], v[130:131], 0, s[38:39]
	v_lshl_add_u64 v[78:79], v[78:79], 2, v[84:85]
	global_store_dwordx4 v[78:79], v[74:77], off offset:64 nt

.LBB0_677:
	s_andn2_b64 vcc, exec, s[68:69]
	s_cbranch_vccnz .LBB0_681
	s_andn2_b64 vcc, exec, s[30:31]
	s_cbranch_vccnz .LBB0_680
	v_readlane_b32 s29, v254, 24
	s_add_u32 s68, s29, s42
	v_readlane_b32 s29, v254, 25
	s_addc_u32 s69, s29, s43
	v_lshlrev_b32_e32 v0, 2, v92
	s_ashr_i32 s39, s38, 31
	v_ashrrev_i32_e32 v131, 31, v130
	v_lshl_add_u64 v[74:75], s[68:69], 0, v[0:1]
	v_lshl_add_u64 v[76:77], v[130:131], 0, s[38:39]
	v_lshl_add_u64 v[74:75], v[76:77], 2, v[74:75]
	global_store_dwordx4 v[74:75], v[70:73], off offset:128 nt

.LBB0_685:
	s_andn2_b64 vcc, exec, s[68:69]
	s_cbranch_vccnz .LBB0_689
	v_cmp_gt_i32_e32 vcc, 32, v140
	s_and_saveexec_b64 s[68:69], vcc
	s_cbranch_execz .LBB0_688
	s_ashr_i32 s39, s38, 31
	v_ashrrev_i32_e32 v131, 31, v130
	v_lshl_add_u64 v[74:75], v[130:131], 0, s[38:39]
	v_lshl_add_u64 v[74:75], v[74:75], 2, v[84:85]
	global_store_dwordx4 v[74:75], v[70:73], off offset:128 nt

.LBB0_709:
	s_andn2_b64 vcc, exec, s[6:7]
	s_cbranch_vccnz .LBB0_713
	s_andn2_b64 vcc, exec, s[30:31]
	s_cbranch_vccnz .LBB0_712
	v_readlane_b32 s6, v254, 24
	s_add_u32 s6, s6, s42
	v_readlane_b32 s7, v254, 25
	s_addc_u32 s7, s7, s43
	v_lshlrev_b32_e32 v0, 2, v92
	s_ashr_i32 s39, s38, 31
	v_ashrrev_i32_e32 v131, 31, v130
	v_lshl_add_u64 v[70:71], s[6:7], 0, v[0:1]
	v_lshl_add_u64 v[72:73], v[130:131], 0, s[38:39]
	v_lshl_add_u64 v[70:71], v[72:73], 2, v[70:71]
	global_store_dwordx4 v[70:71], v[66:69], off offset:192 nt

.LBB0_717:
	s_andn2_b64 vcc, exec, s[6:7]
	s_cbranch_vccnz .LBB0_721
	v_cmp_gt_i32_e32 vcc, 32, v126
	s_and_saveexec_b64 s[6:7], vcc
	s_cbranch_execz .LBB0_720
	s_ashr_i32 s39, s38, 31
	v_ashrrev_i32_e32 v131, 31, v130
	v_lshl_add_u64 v[70:71], v[130:131], 0, s[38:39]
	v_lshl_add_u64 v[70:71], v[70:71], 2, v[84:85]
	global_store_dwordx4 v[70:71], v[66:69], off offset:192 nt

.LBB0_738:
	v_lshlrev_b32_e32 v0, 3, v146
	v_and_b32_e32 v0, 0x78, v0
	v_lshlrev_b32_e32 v0, 1, v0
	v_mad_u64_u32 v[66:67], s[6:7], v70, s30, v[0:1]
	v_lshl_add_u64 v[70:71], v[68:69], 0, v[0:1]
	ds_read_b128 v[66:69], v66
	s_mov_b64 s[28:29], -1
	s_andn2_b64 vcc, exec, s[36:37]
	s_waitcnt lgkmcnt(0)
	global_store_dwordx4 v[70:71], v[66:69], off nt
	s_nop 1
	v_add_u32_e32 v66, 0x100, v146
	v_ashrrev_i32_e32 v70, 4, v66
	v_cndmask_b32_e64 v67, 0, 1, s[36:37]
	v_add_u32_e32 v66, s13, v70
	v_cmp_ne_u32_e64 s[6:7], 1, v67
	s_cbranch_vccnz .LBB0_740
	v_mov_b64_e32 v[68:69], s[10:11]
	v_mad_i64_i32 v[68:69], s[28:29], v66, s33, v[68:69]
	s_mov_b64 s[28:29], 0

.LBB0_745:
	v_mad_u64_u32 v[66:67], s[28:29], v70, s30, v[0:1]
	v_lshl_add_u64 v[70:71], v[68:69], 0, v[0:1]
	ds_read_b128 v[66:69], v66
	s_mov_b64 s[28:29], -1
	s_and_b64 vcc, exec, s[6:7]
	s_waitcnt lgkmcnt(0)
	global_store_dwordx4 v[70:71], v[66:69], off nt
	s_nop 1
	v_add_u32_e32 v66, 0x200, v146
	v_ashrrev_i32_e32 v70, 4, v66
	v_add_u32_e32 v66, s13, v70
	s_cbranch_vccnz .LBB0_747
	v_mov_b64_e32 v[68:69], s[10:11]
	v_mad_i64_i32 v[68:69], s[28:29], v66, s33, v[68:69]
	s_mov_b64 s[28:29], 0

.LBB0_752:
	v_mad_u64_u32 v[66:67], s[28:29], v70, s30, v[0:1]
	v_lshl_add_u64 v[70:71], v[68:69], 0, v[0:1]
	ds_read_b128 v[66:69], v66
	s_mov_b64 s[28:29], -1
	s_and_b64 vcc, exec, s[6:7]
	s_waitcnt lgkmcnt(0)
	global_store_dwordx4 v[70:71], v[66:69], off nt
	s_nop 1
	v_add_u32_e32 v66, 0x300, v146
	v_ashrrev_i32_e32 v70, 4, v66
	v_add_u32_e32 v66, s13, v70
	s_cbranch_vccnz .LBB0_754
	v_mov_b64_e32 v[68:69], s[10:11]
	v_mad_i64_i32 v[68:69], s[28:29], v66, s33, v[68:69]
	s_mov_b64 s[28:29], 0

.LBB0_759:
	v_mad_u64_u32 v[66:67], s[28:29], v70, s30, v[0:1]
	v_lshl_add_u64 v[70:71], v[68:69], 0, v[0:1]
	ds_read_b128 v[66:69], v66
	s_mov_b64 s[28:29], -1
	s_and_b64 vcc, exec, s[6:7]
	s_waitcnt lgkmcnt(0)
	global_store_dwordx4 v[70:71], v[66:69], off nt
	s_nop 1
	v_add_u32_e32 v66, 0x400, v146
	v_ashrrev_i32_e32 v70, 4, v66
	v_add_u32_e32 v66, s13, v70
	s_cbranch_vccnz .LBB0_761
	v_mov_b64_e32 v[68:69], s[10:11]
	v_mad_i64_i32 v[68:69], s[28:29], v66, s33, v[68:69]
	s_mov_b64 s[28:29], 0

.LBB0_766:
	v_mad_u64_u32 v[66:67], s[28:29], v70, s30, v[0:1]
	v_lshl_add_u64 v[70:71], v[68:69], 0, v[0:1]
	ds_read_b128 v[66:69], v66
	s_mov_b64 s[28:29], -1
	s_and_b64 vcc, exec, s[6:7]
	s_waitcnt lgkmcnt(0)
	global_store_dwordx4 v[70:71], v[66:69], off nt
	s_nop 1
	v_add_u32_e32 v66, 0x500, v146
	v_ashrrev_i32_e32 v70, 4, v66
	v_add_u32_e32 v66, s13, v70
	s_cbranch_vccnz .LBB0_768
	v_mov_b64_e32 v[68:69], s[10:11]
	v_mad_i64_i32 v[68:69], s[28:29], v66, s33, v[68:69]
	s_mov_b64 s[28:29], 0

.LBB0_773:
	v_mad_u64_u32 v[66:67], s[28:29], v70, s30, v[0:1]
	v_lshl_add_u64 v[70:71], v[68:69], 0, v[0:1]
	ds_read_b128 v[66:69], v66
	s_mov_b64 s[28:29], -1
	s_and_b64 vcc, exec, s[6:7]
	s_waitcnt lgkmcnt(0)
	global_store_dwordx4 v[70:71], v[66:69], off nt
	s_nop 1
	v_add_u32_e32 v66, 0x600, v146
	v_ashrrev_i32_e32 v70, 4, v66
	v_add_u32_e32 v66, s13, v70
	s_cbranch_vccnz .LBB0_775
	v_mov_b64_e32 v[68:69], s[10:11]
	v_mad_i64_i32 v[68:69], s[28:29], v66, s33, v[68:69]
	s_mov_b64 s[28:29], 0

.LBB0_780:
	v_mad_u64_u32 v[66:67], s[28:29], v70, s30, v[0:1]
	v_lshl_add_u64 v[70:71], v[68:69], 0, v[0:1]
	ds_read_b128 v[66:69], v66
	s_mov_b64 s[28:29], -1
	s_and_b64 vcc, exec, s[6:7]
	s_waitcnt lgkmcnt(0)
	global_store_dwordx4 v[70:71], v[66:69], off nt
	s_nop 1
	v_add_u32_e32 v66, 0x700, v146
	v_ashrrev_i32_e32 v70, 4, v66
	v_add_u32_e32 v66, s13, v70
	s_cbranch_vccnz .LBB0_782
	v_mov_b64_e32 v[68:69], s[10:11]
	v_mad_i64_i32 v[68:69], s[6:7], v66, s33, v[68:69]
	s_mov_b64 s[28:29], 0

.LBB0_787:
	v_mad_u64_u32 v[66:67], s[4:5], v70, s30, v[0:1]
	v_lshl_add_u64 v[70:71], v[68:69], 0, v[0:1]
	ds_read_b128 v[66:69], v66
	s_waitcnt lgkmcnt(0)
	global_store_dwordx4 v[70:71], v[66:69], off nt
